# v83 plus s_waitcnt vmcnt(0) at the GLA item tail so no prefetch load of the stream loop can land in a register of the next work item
# speedup vs baseline: 1.0011x; 1.0011x over previous
.Lgla_tail:
	ds_read2_b32 v[104:105], v150 offset0:0 offset1:32
	ds_read2_b32 v[106:107], v150 offset0:64 offset1:96
	ds_read2_b32 v[108:109], v150 offset0:128 offset1:160
	ds_read2_b32 v[110:111], v150 offset0:192 offset1:224
	s_waitcnt lgkmcnt(0)
	v_add_f32_e32 v112, v104, v105
	v_add_f32_e32 v112, v112, v106
	v_add_f32_e32 v112, v112, v107
	v_add_f32_e32 v112, v112, v108
	v_add_f32_e32 v112, v112, v109
	v_add_f32_e32 v112, v112, v110
	v_add_f32_e32 v112, v112, v111
	v_mul_f32_e32 v113, v112, v112
	v_cvt_pk_bf16_f32 v116, v112, v129
	v_mov_b32_e32 v117, v112
	v_mov_b32_e32 v118, v113
	global_store_short v132, v116, s[10:11]
	s_nop 1
	v_permlane16_swap_b32_e32 v112, v117
	v_permlane16_swap_b32_e32 v113, v118
	v_add_f32_e32 v112, v112, v117
	v_add_f32_e32 v113, v113, v118
	s_nop 1
	v_add_f32_dpp v112, v112, v112 row_ror:8 row_mask:0xf bank_mask:0xf
	v_add_f32_dpp v113, v113, v113 row_ror:8 row_mask:0xf bank_mask:0xf
	s_nop 1
	v_add_f32_dpp v112, v112, v112 row_ror:4 row_mask:0xf bank_mask:0xf
	v_add_f32_dpp v113, v113, v113 row_ror:4 row_mask:0xf bank_mask:0xf
	s_nop 1
	v_add_f32_dpp v112, v112, v112 row_ror:2 row_mask:0xf bank_mask:0xf
	v_add_f32_dpp v113, v113, v113 row_ror:2 row_mask:0xf bank_mask:0xf
	s_nop 1
	v_add_f32_dpp v112, v112, v112 row_ror:1 row_mask:0xf bank_mask:0xf
	v_add_f32_dpp v113, v113, v113 row_ror:1 row_mask:0xf bank_mask:0xf
	v_mov_b32_e32 v114, 0
	v_mov_b32_e32 v115, 0
	s_mov_b64 exec, s[18:19]
	global_store_dwordx4 v133, v[112:115], s[12:13]
	s_mov_b64 exec, -1
	s_mov_b32 s20, 0x10000
	s_movk_i32 s21, 0x1000
	s_add_u32 s10, s10, s20
	s_addc_u32 s11, s11, 0
	s_add_u32 s12, s12, s21
	s_addc_u32 s13, s13, 0
	s_waitcnt vmcnt(0)
	s_branch .LBB0_183
